# attention softmax denominator as four independent partial sums (v206/v208 reused as accumulators) instead of two
# speedup vs baseline: 1.0285x; 1.0096x over previous
.Latt3_nr_5:
	v_exp_f32_e32 v82, v82
	v_exp_f32_e32 v83, v83
	v_exp_f32_e32 v84, v84
	v_exp_f32_e32 v85, v85
	v_exp_f32_e32 v86, v86
	v_exp_f32_e32 v87, v87
	v_exp_f32_e32 v88, v88
	v_exp_f32_e32 v89, v89
	v_cvt_pk_bf16_f32 v226, v82, v83
	v_cvt_pk_bf16_f32 v227, v84, v85
	v_cvt_pk_bf16_f32 v228, v86, v87
	v_cvt_pk_bf16_f32 v229, v88, v89
	s_nop 1
	s_waitcnt lgkmcnt(4)
	v_mfma_f32_32x32x16_bf16 v[50:65], v[236:239], v[226:229], v[50:65]
	ds_read_b128 v[236:239], v205 offset:30240
	v_exp_f32_e32 v90, v90
	v_exp_f32_e32 v91, v91
	v_exp_f32_e32 v92, v92
	v_exp_f32_e32 v93, v93
	s_waitcnt lgkmcnt(4)
	v_mfma_f32_32x32x16_bf16 v[34:49], v[240:243], v[226:229], v[34:49]
	ds_read_b128 v[240:243], v205 offset:34848
	v_exp_f32_e32 v94, v94
	v_exp_f32_e32 v95, v95
	v_exp_f32_e32 v96, v96
	v_exp_f32_e32 v97, v97
	s_waitcnt lgkmcnt(4)
	v_mfma_f32_32x32x16_bf16 v[18:33], v[244:247], v[226:229], v[18:33]
	ds_read_b128 v[244:247], v205 offset:39456
	v_add_f32_e32 v186, 0, v82
	v_add_f32_e32 v206, 0, v84
	v_add_f32_e32 v187, 0, v86
	v_add_f32_e32 v208, 0, v88
	s_waitcnt lgkmcnt(4)
	v_mfma_f32_32x32x16_bf16 v[2:17], v[248:251], v[226:229], v[2:17]
	ds_read_b128 v[248:251], v205 offset:25664
	v_add_f32_e32 v186, v83, v186
	v_add_f32_e32 v206, v85, v206
	v_add_f32_e32 v187, v87, v187
	v_add_f32_e32 v208, v89, v208
	v_cvt_pk_bf16_f32 v226, v90, v91
	v_cvt_pk_bf16_f32 v227, v92, v93
	v_cvt_pk_bf16_f32 v228, v94, v95
	v_cvt_pk_bf16_f32 v229, v96, v97
	s_nop 1
	s_waitcnt lgkmcnt(4)
	v_mfma_f32_32x32x16_bf16 v[50:65], v[210:213], v[226:229], v[50:65]
	ds_read_b128 v[210:213], v205 offset:30272
	v_exp_f32_e32 v66, v66
	v_exp_f32_e32 v67, v67
	v_exp_f32_e32 v68, v68
	v_exp_f32_e32 v69, v69
	s_waitcnt lgkmcnt(4)
	v_mfma_f32_32x32x16_bf16 v[34:49], v[236:239], v[226:229], v[34:49]
	ds_read_b128 v[236:239], v205 offset:34880
	v_exp_f32_e32 v70, v70
	v_exp_f32_e32 v71, v71
	v_exp_f32_e32 v72, v72
	v_exp_f32_e32 v73, v73
	s_waitcnt lgkmcnt(4)
	v_mfma_f32_32x32x16_bf16 v[18:33], v[240:243], v[226:229], v[18:33]
	ds_read_b128 v[240:243], v205 offset:39488
	v_add_f32_e32 v186, v90, v186
	v_add_f32_e32 v206, v92, v206
	v_add_f32_e32 v187, v94, v187
	v_add_f32_e32 v208, v96, v208
	s_waitcnt lgkmcnt(4)
	v_mfma_f32_32x32x16_bf16 v[2:17], v[244:247], v[226:229], v[2:17]
	ds_read_b128 v[244:247], v205 offset:25696
	v_add_f32_e32 v186, v91, v186
	v_add_f32_e32 v206, v93, v206
	v_add_f32_e32 v187, v95, v187
	v_add_f32_e32 v208, v97, v208
	v_cvt_pk_bf16_f32 v226, v66, v67
	v_cvt_pk_bf16_f32 v227, v68, v69
	v_cvt_pk_bf16_f32 v228, v70, v71
	v_cvt_pk_bf16_f32 v229, v72, v73
	s_nop 1
	s_waitcnt lgkmcnt(4)
	v_mfma_f32_32x32x16_bf16 v[50:65], v[248:251], v[226:229], v[50:65]
	ds_read_b128 v[248:251], v205 offset:30304
	v_exp_f32_e32 v74, v74
	v_exp_f32_e32 v75, v75
	v_exp_f32_e32 v76, v76
	v_exp_f32_e32 v77, v77
	s_waitcnt lgkmcnt(4)
	v_mfma_f32_32x32x16_bf16 v[34:49], v[210:213], v[226:229], v[34:49]
	ds_read_b128 v[210:213], v205 offset:34912
	v_exp_f32_e32 v78, v78
	v_exp_f32_e32 v79, v79
	v_exp_f32_e32 v80, v80
	v_exp_f32_e32 v81, v81
	s_waitcnt lgkmcnt(4)
	v_mfma_f32_32x32x16_bf16 v[18:33], v[236:239], v[226:229], v[18:33]
	ds_read_b128 v[236:239], v205 offset:39520
	v_add_f32_e32 v186, v66, v186
	v_add_f32_e32 v206, v68, v206
	v_add_f32_e32 v187, v70, v187
	v_add_f32_e32 v208, v72, v208
	s_waitcnt lgkmcnt(4)
	v_mfma_f32_32x32x16_bf16 v[2:17], v[240:243], v[226:229], v[2:17]
	v_add_f32_e32 v186, v67, v186
	v_add_f32_e32 v206, v69, v206
	v_add_f32_e32 v187, v71, v187
	v_add_f32_e32 v208, v73, v208
	v_cvt_pk_bf16_f32 v226, v74, v75
	v_cvt_pk_bf16_f32 v227, v76, v77
	v_cvt_pk_bf16_f32 v228, v78, v79
	v_cvt_pk_bf16_f32 v229, v80, v81
	s_nop 1
	s_waitcnt lgkmcnt(3)
	v_mfma_f32_32x32x16_bf16 v[50:65], v[244:247], v[226:229], v[50:65]
	v_add_f32_e32 v186, v74, v186
	v_add_f32_e32 v206, v76, v206
	s_waitcnt lgkmcnt(2)
	v_mfma_f32_32x32x16_bf16 v[34:49], v[248:251], v[226:229], v[34:49]
	v_add_f32_e32 v187, v78, v187
	v_add_f32_e32 v208, v80, v208
	s_waitcnt lgkmcnt(1)
	v_mfma_f32_32x32x16_bf16 v[18:33], v[210:213], v[226:229], v[18:33]
	v_add_f32_e32 v186, v75, v186
	v_add_f32_e32 v206, v77, v206
	s_waitcnt lgkmcnt(0)
	s_barrier
	v_mfma_f32_32x32x16_bf16 v[2:17], v[236:239], v[226:229], v[2:17]
	v_add_f32_e32 v187, v79, v187
	v_add_f32_e32 v208, v81, v208
	v_add_f32_e32 v186, v186, v206
	v_add_f32_e32 v187, v187, v208
	v_add_f32_e32 v186, v186, v187
	v_add_f32_e32 v225, v224, v186
	s_setprio 0
	s_add_i32 s13, s11, 2
	s_cmp_ge_u32 s13, s5
	s_cbranch_scc1 .Latt3_wskip_6
	v_add_u32_e32 v206, s72, v219
	v_add_u32_e32 v208, s72, v220
	v_add_u32_e32 v186, s72, v221
	v_add_u32_e32 v187, s72, v222
	s_add_i32 s13, s11, 3
	s_cmp_ge_u32 s13, s5
	s_cbranch_scc1 .Latt3_wtail_7
	s_waitcnt vmcnt(9)
	ds_write_b128 v206, v[118:121]
	s_waitcnt vmcnt(8)
	ds_write_b128 v208, v[122:125]
	s_waitcnt vmcnt(7)
	ds_write_b128 v186, v[130:133]
	s_waitcnt vmcnt(6)
	ds_write_b128 v187, v[134:137] offset:25600
	s_waitcnt vmcnt(5)
	ds_write_b128 v187, v[138:141] offset:34816
	s_branch .Latt3_wld_8

.Latt3_nr_10:
	v_exp_f32_e32 v82, v82
	v_exp_f32_e32 v83, v83
	v_exp_f32_e32 v84, v84
	v_exp_f32_e32 v85, v85
	v_exp_f32_e32 v86, v86
	v_exp_f32_e32 v87, v87
	v_exp_f32_e32 v88, v88
	v_exp_f32_e32 v89, v89
	v_cvt_pk_bf16_f32 v226, v82, v83
	v_cvt_pk_bf16_f32 v227, v84, v85
	v_cvt_pk_bf16_f32 v228, v86, v87
	v_cvt_pk_bf16_f32 v229, v88, v89
	s_nop 1
	s_waitcnt lgkmcnt(4)
	v_mfma_f32_32x32x16_bf16 v[50:65], v[236:239], v[226:229], v[50:65]
	ds_read_b128 v[236:239], v205 offset:30240
	v_exp_f32_e32 v90, v90
	v_exp_f32_e32 v91, v91
	v_exp_f32_e32 v92, v92
	v_exp_f32_e32 v93, v93
	s_waitcnt lgkmcnt(4)
	v_mfma_f32_32x32x16_bf16 v[34:49], v[240:243], v[226:229], v[34:49]
	ds_read_b128 v[240:243], v205 offset:34848
	v_exp_f32_e32 v94, v94
	v_exp_f32_e32 v95, v95
	v_exp_f32_e32 v96, v96
	v_exp_f32_e32 v97, v97
	s_waitcnt lgkmcnt(4)
	v_mfma_f32_32x32x16_bf16 v[18:33], v[244:247], v[226:229], v[18:33]
	ds_read_b128 v[244:247], v205 offset:39456
	v_add_f32_e32 v186, 0, v82
	v_add_f32_e32 v206, 0, v84
	v_add_f32_e32 v187, 0, v86
	v_add_f32_e32 v208, 0, v88
	s_waitcnt lgkmcnt(4)
	v_mfma_f32_32x32x16_bf16 v[2:17], v[248:251], v[226:229], v[2:17]
	ds_read_b128 v[248:251], v205 offset:25664
	v_add_f32_e32 v186, v83, v186
	v_add_f32_e32 v206, v85, v206
	v_add_f32_e32 v187, v87, v187
	v_add_f32_e32 v208, v89, v208
	v_cvt_pk_bf16_f32 v226, v90, v91
	v_cvt_pk_bf16_f32 v227, v92, v93
	v_cvt_pk_bf16_f32 v228, v94, v95
	v_cvt_pk_bf16_f32 v229, v96, v97
	s_nop 1
	s_waitcnt lgkmcnt(4)
	v_mfma_f32_32x32x16_bf16 v[50:65], v[210:213], v[226:229], v[50:65]
	ds_read_b128 v[210:213], v205 offset:30272
	v_exp_f32_e32 v66, v66
	v_exp_f32_e32 v67, v67
	v_exp_f32_e32 v68, v68
	v_exp_f32_e32 v69, v69
	s_waitcnt lgkmcnt(4)
	v_mfma_f32_32x32x16_bf16 v[34:49], v[236:239], v[226:229], v[34:49]
	ds_read_b128 v[236:239], v205 offset:34880
	v_exp_f32_e32 v70, v70
	v_exp_f32_e32 v71, v71
	v_exp_f32_e32 v72, v72
	v_exp_f32_e32 v73, v73
	s_waitcnt lgkmcnt(4)
	v_mfma_f32_32x32x16_bf16 v[18:33], v[240:243], v[226:229], v[18:33]
	ds_read_b128 v[240:243], v205 offset:39488
	v_add_f32_e32 v186, v90, v186
	v_add_f32_e32 v206, v92, v206
	v_add_f32_e32 v187, v94, v187
	v_add_f32_e32 v208, v96, v208
	s_waitcnt lgkmcnt(4)
	v_mfma_f32_32x32x16_bf16 v[2:17], v[244:247], v[226:229], v[2:17]
	ds_read_b128 v[244:247], v205 offset:25696
	v_add_f32_e32 v186, v91, v186
	v_add_f32_e32 v206, v93, v206
	v_add_f32_e32 v187, v95, v187
	v_add_f32_e32 v208, v97, v208
	v_cvt_pk_bf16_f32 v226, v66, v67
	v_cvt_pk_bf16_f32 v227, v68, v69
	v_cvt_pk_bf16_f32 v228, v70, v71
	v_cvt_pk_bf16_f32 v229, v72, v73
	s_nop 1
	s_waitcnt lgkmcnt(4)
	v_mfma_f32_32x32x16_bf16 v[50:65], v[248:251], v[226:229], v[50:65]
	ds_read_b128 v[248:251], v205 offset:30304
	v_exp_f32_e32 v74, v74
	v_exp_f32_e32 v75, v75
	v_exp_f32_e32 v76, v76
	v_exp_f32_e32 v77, v77
	s_waitcnt lgkmcnt(4)
	v_mfma_f32_32x32x16_bf16 v[34:49], v[210:213], v[226:229], v[34:49]
	ds_read_b128 v[210:213], v205 offset:34912
	v_exp_f32_e32 v78, v78
	v_exp_f32_e32 v79, v79
	v_exp_f32_e32 v80, v80
	v_exp_f32_e32 v81, v81
	s_waitcnt lgkmcnt(4)
	v_mfma_f32_32x32x16_bf16 v[18:33], v[236:239], v[226:229], v[18:33]
	ds_read_b128 v[236:239], v205 offset:39520
	v_add_f32_e32 v186, v66, v186
	v_add_f32_e32 v206, v68, v206
	v_add_f32_e32 v187, v70, v187
	v_add_f32_e32 v208, v72, v208
	s_waitcnt lgkmcnt(4)
	v_mfma_f32_32x32x16_bf16 v[2:17], v[240:243], v[226:229], v[2:17]
	v_add_f32_e32 v186, v67, v186
	v_add_f32_e32 v206, v69, v206
	v_add_f32_e32 v187, v71, v187
	v_add_f32_e32 v208, v73, v208
	v_cvt_pk_bf16_f32 v226, v74, v75
	v_cvt_pk_bf16_f32 v227, v76, v77
	v_cvt_pk_bf16_f32 v228, v78, v79
	v_cvt_pk_bf16_f32 v229, v80, v81
	s_nop 1
	s_waitcnt lgkmcnt(3)
	v_mfma_f32_32x32x16_bf16 v[50:65], v[244:247], v[226:229], v[50:65]
	v_add_f32_e32 v186, v74, v186
	v_add_f32_e32 v206, v76, v206
	s_waitcnt lgkmcnt(2)
	v_mfma_f32_32x32x16_bf16 v[34:49], v[248:251], v[226:229], v[34:49]
	v_add_f32_e32 v187, v78, v187
	v_add_f32_e32 v208, v80, v208
	s_waitcnt lgkmcnt(1)
	v_mfma_f32_32x32x16_bf16 v[18:33], v[210:213], v[226:229], v[18:33]
	v_add_f32_e32 v186, v75, v186
	v_add_f32_e32 v206, v77, v206
	s_waitcnt lgkmcnt(0)
	s_barrier
	v_mfma_f32_32x32x16_bf16 v[2:17], v[236:239], v[226:229], v[2:17]
	v_add_f32_e32 v187, v79, v187
	v_add_f32_e32 v208, v81, v208
	v_add_f32_e32 v186, v186, v206
	v_add_f32_e32 v187, v187, v208
	v_add_f32_e32 v186, v186, v187
	v_add_f32_e32 v224, v225, v186
	s_setprio 0
	s_add_i32 s13, s11, 2
	s_cmp_ge_u32 s13, s5
	s_cbranch_scc1 .Latt3_wskip_11
	v_add_u32_e32 v206, s72, v219
	v_add_u32_e32 v208, s72, v220
	v_add_u32_e32 v186, s72, v221
	v_add_u32_e32 v187, s72, v222
	s_add_i32 s13, s11, 3
	s_cmp_ge_u32 s13, s5
	s_cbranch_scc1 .Latt3_wtail_12
	s_waitcnt vmcnt(9)
	ds_write_b128 v206, v[102:105]
	s_waitcnt vmcnt(8)
	ds_write_b128 v208, v[106:109]
	s_waitcnt vmcnt(7)
	ds_write_b128 v186, v[114:117]
	s_waitcnt vmcnt(6)
	ds_write_b128 v187, v[98:101] offset:25600
	s_waitcnt vmcnt(5)
	ds_write_b128 v187, v[110:113] offset:34816
	s_branch .Latt3_wld_13

.Latt3_nr_15:
	v_exp_f32_e32 v82, v82
	v_exp_f32_e32 v83, v83
	v_exp_f32_e32 v84, v84
	v_exp_f32_e32 v85, v85
	v_exp_f32_e32 v86, v86
	v_exp_f32_e32 v87, v87
	v_exp_f32_e32 v88, v88
	v_exp_f32_e32 v89, v89
	v_cvt_pk_bf16_f32 v226, v82, v83
	v_cvt_pk_bf16_f32 v227, v84, v85
	v_cvt_pk_bf16_f32 v228, v86, v87
	v_cvt_pk_bf16_f32 v229, v88, v89
	s_nop 1
	s_waitcnt lgkmcnt(4)
	v_mfma_f32_32x32x16_bf16 v[50:65], v[236:239], v[226:229], v[50:65]
	ds_read_b128 v[236:239], v205 offset:30240
	v_exp_f32_e32 v90, v90
	v_exp_f32_e32 v91, v91
	v_exp_f32_e32 v92, v92
	v_exp_f32_e32 v93, v93
	s_waitcnt lgkmcnt(4)
	v_mfma_f32_32x32x16_bf16 v[34:49], v[240:243], v[226:229], v[34:49]
	ds_read_b128 v[240:243], v205 offset:34848
	v_exp_f32_e32 v94, v94
	v_exp_f32_e32 v95, v95
	v_exp_f32_e32 v96, v96
	v_exp_f32_e32 v97, v97
	s_waitcnt lgkmcnt(4)
	v_mfma_f32_32x32x16_bf16 v[18:33], v[244:247], v[226:229], v[18:33]
	ds_read_b128 v[244:247], v205 offset:39456
	v_add_f32_e32 v186, 0, v82
	v_add_f32_e32 v206, 0, v84
	v_add_f32_e32 v187, 0, v86
	v_add_f32_e32 v208, 0, v88
	s_waitcnt lgkmcnt(4)
	v_mfma_f32_32x32x16_bf16 v[2:17], v[248:251], v[226:229], v[2:17]
	ds_read_b128 v[248:251], v205 offset:25664
	v_add_f32_e32 v186, v83, v186
	v_add_f32_e32 v206, v85, v206
	v_add_f32_e32 v187, v87, v187
	v_add_f32_e32 v208, v89, v208
	v_cvt_pk_bf16_f32 v226, v90, v91
	v_cvt_pk_bf16_f32 v227, v92, v93
	v_cvt_pk_bf16_f32 v228, v94, v95
	v_cvt_pk_bf16_f32 v229, v96, v97
	s_nop 1
	s_waitcnt lgkmcnt(4)
	v_mfma_f32_32x32x16_bf16 v[50:65], v[210:213], v[226:229], v[50:65]
	ds_read_b128 v[210:213], v205 offset:30272
	v_exp_f32_e32 v66, v66
	v_exp_f32_e32 v67, v67
	v_exp_f32_e32 v68, v68
	v_exp_f32_e32 v69, v69
	s_waitcnt lgkmcnt(4)
	v_mfma_f32_32x32x16_bf16 v[34:49], v[236:239], v[226:229], v[34:49]
	ds_read_b128 v[236:239], v205 offset:34880
	v_exp_f32_e32 v70, v70
	v_exp_f32_e32 v71, v71
	v_exp_f32_e32 v72, v72
	v_exp_f32_e32 v73, v73
	s_waitcnt lgkmcnt(4)
	v_mfma_f32_32x32x16_bf16 v[18:33], v[240:243], v[226:229], v[18:33]
	ds_read_b128 v[240:243], v205 offset:39488
	v_add_f32_e32 v186, v90, v186
	v_add_f32_e32 v206, v92, v206
	v_add_f32_e32 v187, v94, v187
	v_add_f32_e32 v208, v96, v208
	s_waitcnt lgkmcnt(4)
	v_mfma_f32_32x32x16_bf16 v[2:17], v[244:247], v[226:229], v[2:17]
	ds_read_b128 v[244:247], v205 offset:25696
	v_add_f32_e32 v186, v91, v186
	v_add_f32_e32 v206, v93, v206
	v_add_f32_e32 v187, v95, v187
	v_add_f32_e32 v208, v97, v208
	v_cvt_pk_bf16_f32 v226, v66, v67
	v_cvt_pk_bf16_f32 v227, v68, v69
	v_cvt_pk_bf16_f32 v228, v70, v71
	v_cvt_pk_bf16_f32 v229, v72, v73
	s_nop 1
	s_waitcnt lgkmcnt(4)
	v_mfma_f32_32x32x16_bf16 v[50:65], v[248:251], v[226:229], v[50:65]
	ds_read_b128 v[248:251], v205 offset:30304
	v_exp_f32_e32 v74, v74
	v_exp_f32_e32 v75, v75
	v_exp_f32_e32 v76, v76
	v_exp_f32_e32 v77, v77
	s_waitcnt lgkmcnt(4)
	v_mfma_f32_32x32x16_bf16 v[34:49], v[210:213], v[226:229], v[34:49]
	ds_read_b128 v[210:213], v205 offset:34912
	v_exp_f32_e32 v78, v78
	v_exp_f32_e32 v79, v79
	v_exp_f32_e32 v80, v80
	v_exp_f32_e32 v81, v81
	s_waitcnt lgkmcnt(4)
	v_mfma_f32_32x32x16_bf16 v[18:33], v[236:239], v[226:229], v[18:33]
	ds_read_b128 v[236:239], v205 offset:39520
	v_add_f32_e32 v186, v66, v186
	v_add_f32_e32 v206, v68, v206
	v_add_f32_e32 v187, v70, v187
	v_add_f32_e32 v208, v72, v208
	s_waitcnt lgkmcnt(4)
	v_mfma_f32_32x32x16_bf16 v[2:17], v[240:243], v[226:229], v[2:17]
	v_add_f32_e32 v186, v67, v186
	v_add_f32_e32 v206, v69, v206
	v_add_f32_e32 v187, v71, v187
	v_add_f32_e32 v208, v73, v208
	v_cvt_pk_bf16_f32 v226, v74, v75
	v_cvt_pk_bf16_f32 v227, v76, v77
	v_cvt_pk_bf16_f32 v228, v78, v79
	v_cvt_pk_bf16_f32 v229, v80, v81
	s_nop 1
	s_waitcnt lgkmcnt(3)
	v_mfma_f32_32x32x16_bf16 v[50:65], v[244:247], v[226:229], v[50:65]
	v_add_f32_e32 v186, v74, v186
	v_add_f32_e32 v206, v76, v206
	s_waitcnt lgkmcnt(2)
	v_mfma_f32_32x32x16_bf16 v[34:49], v[248:251], v[226:229], v[34:49]
	v_add_f32_e32 v187, v78, v187
	v_add_f32_e32 v208, v80, v208
	s_waitcnt lgkmcnt(1)
	v_mfma_f32_32x32x16_bf16 v[18:33], v[210:213], v[226:229], v[18:33]
	v_add_f32_e32 v186, v75, v186
	v_add_f32_e32 v206, v77, v206
	s_waitcnt lgkmcnt(0)
	v_mfma_f32_32x32x16_bf16 v[2:17], v[236:239], v[226:229], v[2:17]
	v_add_f32_e32 v187, v79, v187
	v_add_f32_e32 v208, v81, v208
	v_add_f32_e32 v186, v186, v206
	v_add_f32_e32 v187, v187, v208
	v_add_f32_e32 v186, v186, v187
	v_add_f32_e32 v225, v224, v186
	s_setprio 0
	s_add_i32 s13, s11, 2
	s_cmp_ge_u32 s13, s5
	s_cbranch_scc1 .Latt3_wskip_16
	v_add_u32_e32 v206, s72, v219
	v_add_u32_e32 v208, s72, v220
	v_add_u32_e32 v186, s72, v221
	v_add_u32_e32 v187, s72, v222
	s_add_i32 s13, s11, 3
	s_cmp_ge_u32 s13, s5
	s_cbranch_scc1 .Latt3_wtail_17
	s_waitcnt vmcnt(9)
	ds_write_b128 v206, v[118:121]
	s_waitcnt vmcnt(8)
	ds_write_b128 v208, v[122:125]
	s_waitcnt vmcnt(7)
	ds_write_b128 v186, v[130:133]
	s_waitcnt vmcnt(6)
	ds_write_b128 v187, v[134:137] offset:25600
	s_waitcnt vmcnt(5)
	ds_write_b128 v187, v[138:141] offset:34816
	s_branch .Latt3_wld_18

.Latt3_nr_20:
	v_exp_f32_e32 v82, v82
	v_exp_f32_e32 v83, v83
	v_exp_f32_e32 v84, v84
	v_exp_f32_e32 v85, v85
	v_exp_f32_e32 v86, v86
	v_exp_f32_e32 v87, v87
	v_exp_f32_e32 v88, v88
	v_exp_f32_e32 v89, v89
	v_cvt_pk_bf16_f32 v226, v82, v83
	v_cvt_pk_bf16_f32 v227, v84, v85
	v_cvt_pk_bf16_f32 v228, v86, v87
	v_cvt_pk_bf16_f32 v229, v88, v89
	s_nop 1
	s_waitcnt lgkmcnt(4)
	v_mfma_f32_32x32x16_bf16 v[50:65], v[236:239], v[226:229], v[50:65]
	ds_read_b128 v[236:239], v205 offset:30240
	v_exp_f32_e32 v90, v90
	v_exp_f32_e32 v91, v91
	v_exp_f32_e32 v92, v92
	v_exp_f32_e32 v93, v93
	s_waitcnt lgkmcnt(4)
	v_mfma_f32_32x32x16_bf16 v[34:49], v[240:243], v[226:229], v[34:49]
	ds_read_b128 v[240:243], v205 offset:34848
	v_exp_f32_e32 v94, v94
	v_exp_f32_e32 v95, v95
	v_exp_f32_e32 v96, v96
	v_exp_f32_e32 v97, v97
	s_waitcnt lgkmcnt(4)
	v_mfma_f32_32x32x16_bf16 v[18:33], v[244:247], v[226:229], v[18:33]
	ds_read_b128 v[244:247], v205 offset:39456
	v_add_f32_e32 v186, 0, v82
	v_add_f32_e32 v206, 0, v84
	v_add_f32_e32 v187, 0, v86
	v_add_f32_e32 v208, 0, v88
	s_waitcnt lgkmcnt(4)
	v_mfma_f32_32x32x16_bf16 v[2:17], v[248:251], v[226:229], v[2:17]
	ds_read_b128 v[248:251], v205 offset:25664
	v_add_f32_e32 v186, v83, v186
	v_add_f32_e32 v206, v85, v206
	v_add_f32_e32 v187, v87, v187
	v_add_f32_e32 v208, v89, v208
	v_cvt_pk_bf16_f32 v226, v90, v91
	v_cvt_pk_bf16_f32 v227, v92, v93
	v_cvt_pk_bf16_f32 v228, v94, v95
	v_cvt_pk_bf16_f32 v229, v96, v97
	s_nop 1
	s_waitcnt lgkmcnt(4)
	v_mfma_f32_32x32x16_bf16 v[50:65], v[210:213], v[226:229], v[50:65]
	ds_read_b128 v[210:213], v205 offset:30272
	v_exp_f32_e32 v66, v66
	v_exp_f32_e32 v67, v67
	v_exp_f32_e32 v68, v68
	v_exp_f32_e32 v69, v69
	s_waitcnt lgkmcnt(4)
	v_mfma_f32_32x32x16_bf16 v[34:49], v[236:239], v[226:229], v[34:49]
	ds_read_b128 v[236:239], v205 offset:34880
	v_exp_f32_e32 v70, v70
	v_exp_f32_e32 v71, v71
	v_exp_f32_e32 v72, v72
	v_exp_f32_e32 v73, v73
	s_waitcnt lgkmcnt(4)
	v_mfma_f32_32x32x16_bf16 v[18:33], v[240:243], v[226:229], v[18:33]
	ds_read_b128 v[240:243], v205 offset:39488
	v_add_f32_e32 v186, v90, v186
	v_add_f32_e32 v206, v92, v206
	v_add_f32_e32 v187, v94, v187
	v_add_f32_e32 v208, v96, v208
	s_waitcnt lgkmcnt(4)
	v_mfma_f32_32x32x16_bf16 v[2:17], v[244:247], v[226:229], v[2:17]
	ds_read_b128 v[244:247], v205 offset:25696
	v_add_f32_e32 v186, v91, v186
	v_add_f32_e32 v206, v93, v206
	v_add_f32_e32 v187, v95, v187
	v_add_f32_e32 v208, v97, v208
	v_cvt_pk_bf16_f32 v226, v66, v67
	v_cvt_pk_bf16_f32 v227, v68, v69
	v_cvt_pk_bf16_f32 v228, v70, v71
	v_cvt_pk_bf16_f32 v229, v72, v73
	s_nop 1
	s_waitcnt lgkmcnt(4)
	v_mfma_f32_32x32x16_bf16 v[50:65], v[248:251], v[226:229], v[50:65]
	ds_read_b128 v[248:251], v205 offset:30304
	v_exp_f32_e32 v74, v74
	v_exp_f32_e32 v75, v75
	v_exp_f32_e32 v76, v76
	v_exp_f32_e32 v77, v77
	s_waitcnt lgkmcnt(4)
	v_mfma_f32_32x32x16_bf16 v[34:49], v[210:213], v[226:229], v[34:49]
	ds_read_b128 v[210:213], v205 offset:34912
	v_exp_f32_e32 v78, v78
	v_exp_f32_e32 v79, v79
	v_exp_f32_e32 v80, v80
	v_exp_f32_e32 v81, v81
	s_waitcnt lgkmcnt(4)
	v_mfma_f32_32x32x16_bf16 v[18:33], v[236:239], v[226:229], v[18:33]
	ds_read_b128 v[236:239], v205 offset:39520
	v_add_f32_e32 v186, v66, v186
	v_add_f32_e32 v206, v68, v206
	v_add_f32_e32 v187, v70, v187
	v_add_f32_e32 v208, v72, v208
	s_waitcnt lgkmcnt(4)
	v_mfma_f32_32x32x16_bf16 v[2:17], v[240:243], v[226:229], v[2:17]
	v_add_f32_e32 v186, v67, v186
	v_add_f32_e32 v206, v69, v206
	v_add_f32_e32 v187, v71, v187
	v_add_f32_e32 v208, v73, v208
	v_cvt_pk_bf16_f32 v226, v74, v75
	v_cvt_pk_bf16_f32 v227, v76, v77
	v_cvt_pk_bf16_f32 v228, v78, v79
	v_cvt_pk_bf16_f32 v229, v80, v81
	s_nop 1
	s_waitcnt lgkmcnt(3)
	v_mfma_f32_32x32x16_bf16 v[50:65], v[244:247], v[226:229], v[50:65]
	v_add_f32_e32 v186, v74, v186
	v_add_f32_e32 v206, v76, v206
	s_waitcnt lgkmcnt(2)
	v_mfma_f32_32x32x16_bf16 v[34:49], v[248:251], v[226:229], v[34:49]
	v_add_f32_e32 v187, v78, v187
	v_add_f32_e32 v208, v80, v208
	s_waitcnt lgkmcnt(1)
	v_mfma_f32_32x32x16_bf16 v[18:33], v[210:213], v[226:229], v[18:33]
	v_add_f32_e32 v186, v75, v186
	v_add_f32_e32 v206, v77, v206
	s_waitcnt lgkmcnt(0)
	v_mfma_f32_32x32x16_bf16 v[2:17], v[236:239], v[226:229], v[2:17]
	v_add_f32_e32 v187, v79, v187
	v_add_f32_e32 v208, v81, v208
	v_add_f32_e32 v186, v186, v206
	v_add_f32_e32 v187, v187, v208
	v_add_f32_e32 v186, v186, v187
	v_add_f32_e32 v224, v225, v186
	s_setprio 0
	s_add_i32 s13, s11, 2
	s_cmp_ge_u32 s13, s5
	s_cbranch_scc1 .Latt3_wskip_21
	v_add_u32_e32 v206, s72, v219
	v_add_u32_e32 v208, s72, v220
	v_add_u32_e32 v186, s72, v221
	v_add_u32_e32 v187, s72, v222
	s_add_i32 s13, s11, 3
	s_cmp_ge_u32 s13, s5
	s_cbranch_scc1 .Latt3_wtail_22
	s_waitcnt vmcnt(9)
	ds_write_b128 v206, v[102:105]
	s_waitcnt vmcnt(8)
	ds_write_b128 v208, v[106:109]
	s_waitcnt vmcnt(7)
	ds_write_b128 v186, v[114:117]
	s_waitcnt vmcnt(6)
	ds_write_b128 v187, v[98:101] offset:25600
	s_waitcnt vmcnt(5)
	ds_write_b128 v187, v[110:113] offset:34816
	s_branch .Latt3_wld_23
